# sgu prompt path hand-written, all loads of a unit issued up front, LDS-transposed coalesced epilogue (no cross-unit prefetch)
# speedup vs baseline: 1.0177x; 1.0146x over previous
.LBB0_1405:
	s_cmp_lt_i32 s40, 14
	s_cselect_b64 s[8:9], -1, 0
	s_waitcnt lgkmcnt(0)
	s_and_b64 s[14:15], s[8:9], s[6:7]
	s_andn2_b64 vcc, exec, s[14:15]
	s_cbranch_vccnz .LBB0_1528
	s_mov_b32 s101, s2
	s_cmpk_lt_u32 s101, 0x800
	s_cbranch_scc0 .Lmy_sgu_done
	s_and_b32 s3, s2, 7
	v_readfirstlane_b32 s6, v226
	s_load_dwordx2 s[24:25], s[0:1], 0xc0
	s_load_dwordx2 s[26:27], s[0:1], 0xc8
	s_load_dwordx2 s[28:29], s[0:1], 0xd0
	s_lshr_b32 s6, s6, 6
	s_lshr_b32 s7, s6, 2
	s_and_b32 s6, s6, 3
	v_and_b32_e32 v1, 63, v226
	v_and_b32_e32 v2, 31, v1
	v_lshrrev_b32_e32 v3, 5, v1
	v_and_b32_e32 v4, 0x7f, v226
	v_lshlrev_b32_e32 v4, 2, v4
	s_lshl_b32 s8, s3, 7
	s_lshl_b32 s9, s7, 6
	s_add_i32 s8, s8, s9
	v_add_u32_e32 v5, s8, v2
	v_lshlrev_b32_e32 v14, 2, v5
	s_waitcnt lgkmcnt(0)
	global_load_dword v15, v14, s[24:25] offset:128
	global_load_dword v14, v14, s[24:25]
	s_lshl_b32 s9, s6, 5
	s_lshl_b32 s10, s3, 7
	s_add_i32 s10, s10, s9
	v_lshl_add_u32 v16, v3, 2, s10
	v_lshlrev_b32_e32 v16, 2, v16
	global_load_dword v31, v16, s[28:29] offset:108
	global_load_dword v30, v16, s[28:29] offset:104
	global_load_dword v29, v16, s[28:29] offset:100
	global_load_dword v28, v16, s[28:29] offset:96
	global_load_dword v27, v16, s[28:29] offset:76
	global_load_dword v26, v16, s[28:29] offset:72
	global_load_dword v25, v16, s[28:29] offset:68
	global_load_dword v24, v16, s[28:29] offset:64
	global_load_dword v23, v16, s[28:29] offset:44
	global_load_dword v22, v16, s[28:29] offset:40
	global_load_dword v21, v16, s[28:29] offset:36
	global_load_dword v20, v16, s[28:29] offset:32
	global_load_dword v19, v16, s[28:29] offset:12
	global_load_dword v18, v16, s[28:29] offset:8
	global_load_dword v17, v16, s[28:29] offset:4
	global_load_dword v16, v16, s[28:29]
	s_lshl_b32 s11, s3, 16
	s_lshl_b32 s12, s6, 14
	s_add_i32 s11, s11, s12
	v_lshlrev_b32_e32 v32, 9, v2
	v_lshl_add_u32 v32, v3, 5, v32
	v_add_u32_e32 v32, s11, v32
	global_load_dwordx4 v[92:95], v32, s[26:27] offset:464
	global_load_dwordx4 v[88:91], v32, s[26:27] offset:448
	global_load_dwordx4 v[84:87], v32, s[26:27] offset:400
	global_load_dwordx4 v[80:83], v32, s[26:27] offset:384
	global_load_dwordx4 v[76:79], v32, s[26:27] offset:336
	global_load_dwordx4 v[72:75], v32, s[26:27] offset:320
	global_load_dwordx4 v[68:71], v32, s[26:27] offset:272
	global_load_dwordx4 v[64:67], v32, s[26:27] offset:256
	global_load_dwordx4 v[60:63], v32, s[26:27] offset:208
	global_load_dwordx4 v[56:59], v32, s[26:27] offset:192
	global_load_dwordx4 v[52:55], v32, s[26:27] offset:144
	global_load_dwordx4 v[48:51], v32, s[26:27] offset:128
	global_load_dwordx4 v[44:47], v32, s[26:27] offset:80
	global_load_dwordx4 v[40:43], v32, s[26:27] offset:64
	global_load_dwordx4 v[36:39], v32, s[26:27] offset:16
	global_load_dwordx4 v[32:35], v32, s[26:27]
	v_mov_b32_e32 v6, 0x10600
	v_mul_u32_u24_e32 v5, v5, v6
	v_lshl_add_u32 v5, v3, 4, v5
	v_add_u32_e32 v6, 0x20c000, v5
	v_lshlrev_b32_e32 v7, 5, v3
	s_mul_i32 s12, s6, 0x4200
	s_lshl_b32 s13, s7, 8
	s_add_i32 s12, s12, s13
	s_addk_i32 s12, 0x400
	v_mul_u32_u24_e32 v8, 0x840, v3
	v_lshl_add_u32 v8, v2, 2, v8
	v_add_u32_e32 v8, s12, v8
	v_lshrrev_b32_e32 v9, 4, v226
	v_mul_u32_u24_e32 v9, 0x210, v9
	v_and_b32_e32 v10, 15, v226
	v_lshl_add_u32 v9, v10, 5, v9
	v_add_u32_e32 v9, 0x400, v9
	v_lshrrev_b32_e32 v11, 4, v226
	v_lshlrev_b32_e32 v11, 11, v11
	v_lshl_add_u32 v10, v10, 4, v11
	v_add_u32_e32 v11, 0x10000, v10
	v_add_u32_e32 v12, 0x20000, v10
	v_add_u32_e32 v13, 0x30000, v10
	s_waitcnt vmcnt(30)
.Lmy_sgu_unit:
	s_lshr_b32 s16, s101, 3
	s_lshl_b32 s16, s16, 7
	s_lshl_b32 s17, s16, 2
	s_add_u32 s22, s38, s17
	s_addc_u32 s23, s39, 0
	s_add_u32 s22, s22, 0x3000000
	s_addc_u32 s23, s23, 0
	global_load_dword v204, v4, s[22:23]
	s_add_u32 s22, s22, 0x20c00
	s_addc_u32 s23, s23, 0
	global_load_dword v205, v4, s[22:23]
	s_add_u32 s22, s22, 0x20c00
	s_addc_u32 s23, s23, 0
	global_load_dword v206, v4, s[22:23]
	s_add_u32 s22, s22, 0x20c00
	s_addc_u32 s23, s23, 0
	global_load_dword v207, v4, s[22:23]
	s_add_u32 s22, s22, 0x20c00
	s_addc_u32 s23, s23, 0
	global_load_dword v208, v4, s[22:23]
	s_add_u32 s22, s22, 0x20c00
	s_addc_u32 s23, s23, 0
	global_load_dword v209, v4, s[22:23]
	s_add_u32 s22, s22, 0x20c00
	s_addc_u32 s23, s23, 0
	global_load_dword v210, v4, s[22:23]
	s_add_u32 s22, s22, 0x20c00
	s_addc_u32 s23, s23, 0
	global_load_dword v211, v4, s[22:23]
	s_lshl_b32 s17, s16, 1
	s_add_u32 s18, s38, s17
	s_addc_u32 s19, s39, 0
	s_add_u32 s18, s18, 0xc500000
	s_addc_u32 s19, s19, 0
	global_load_dwordx4 v[96:99], v5, s[18:19]
	global_load_dwordx4 v[128:131], v6, s[18:19]
	global_load_dwordx4 v[100:103], v5, s[18:19] offset:32
	global_load_dwordx4 v[132:135], v6, s[18:19] offset:32
	global_load_dwordx4 v[104:107], v5, s[18:19] offset:64
	global_load_dwordx4 v[136:139], v6, s[18:19] offset:64
	global_load_dwordx4 v[108:111], v5, s[18:19] offset:96
	global_load_dwordx4 v[140:143], v6, s[18:19] offset:96
	global_load_dwordx4 v[112:115], v5, s[18:19] offset:128
	global_load_dwordx4 v[144:147], v6, s[18:19] offset:128
	global_load_dwordx4 v[116:119], v5, s[18:19] offset:160
	global_load_dwordx4 v[148:151], v6, s[18:19] offset:160
	global_load_dwordx4 v[120:123], v5, s[18:19] offset:192
	global_load_dwordx4 v[152:155], v6, s[18:19] offset:192
	global_load_dwordx4 v[124:127], v5, s[18:19] offset:224
	global_load_dwordx4 v[156:159], v6, s[18:19] offset:224
	s_lshl_b32 s17, s16, 11
	s_lshl_b32 s20, s3, 8
	s_add_i32 s17, s17, s20
	s_add_u32 s20, s38, s17
	s_addc_u32 s21, s39, 0
	s_add_u32 s44, s20, 0x10700000
	s_addc_u32 s45, s21, 0
	s_add_u32 s20, s20, 0x8400000
	s_addc_u32 s21, s21, 0
	global_load_dwordx4 v[228:231], v10, s[20:21]
	global_load_dwordx4 v[232:235], v11, s[20:21]
	global_load_dwordx4 v[236:239], v12, s[20:21]
	global_load_dwordx4 v[240:243], v13, s[20:21]
	s_waitcnt vmcnt(20)
	v_add_f32_e32 v204, v204, v205
	v_add_f32_e32 v206, v206, v207
	v_add_f32_e32 v208, v208, v209
	v_add_f32_e32 v210, v210, v211
	v_add_f32_e32 v204, v204, v206
	v_add_f32_e32 v208, v208, v210
	v_add_f32_e32 v204, v204, v208
	v_mov_b32_e32 v205, 0x358637bd
	v_fmac_f32_e32 v205, 0x3a800000, v204
	v_rsq_f32_e32 v205, v205
	v_cmp_gt_u32_e32 vcc, 0x80, v226
	s_and_saveexec_b64 s[8:9], vcc
	ds_write_b32 v4, v205
	s_or_b64 exec, exec, s[8:9]
	s_waitcnt lgkmcnt(0)
	s_barrier
	s_waitcnt vmcnt(4)
	ds_read_b128 v[196:199], v7
	ds_read_b128 v[200:203], v7 offset:16
	s_waitcnt lgkmcnt(0)
	v_mul_f32_e32 v244, v32, v196
	v_mul_f32_e32 v245, v33, v197
	v_mul_f32_e32 v246, v34, v198
	v_mul_f32_e32 v247, v35, v199
	v_mul_f32_e32 v248, v36, v200
	v_mul_f32_e32 v249, v37, v201
	v_mul_f32_e32 v250, v38, v202
	v_mul_f32_e32 v251, v39, v203
	v_cvt_pk_bf16_f32 v192, v244, v245
	v_cvt_pk_bf16_f32 v193, v246, v247
	v_cvt_pk_bf16_f32 v194, v248, v249
	v_cvt_pk_bf16_f32 v195, v250, v251
	s_nop 1
	v_mfma_f32_32x32x16_bf16 v[160:175], v[192:195], v[96:99], 0
	v_mfma_f32_32x32x16_bf16 v[176:191], v[192:195], v[128:131], 0
	ds_read_b128 v[196:199], v7 offset:64
	ds_read_b128 v[200:203], v7 offset:80
	s_waitcnt lgkmcnt(0)
	v_mul_f32_e32 v244, v40, v196
	v_mul_f32_e32 v245, v41, v197
	v_mul_f32_e32 v246, v42, v198
	v_mul_f32_e32 v247, v43, v199
	v_mul_f32_e32 v248, v44, v200
	v_mul_f32_e32 v249, v45, v201
	v_mul_f32_e32 v250, v46, v202
	v_mul_f32_e32 v251, v47, v203
	v_cvt_pk_bf16_f32 v192, v244, v245
	v_cvt_pk_bf16_f32 v193, v246, v247
	v_cvt_pk_bf16_f32 v194, v248, v249
	v_cvt_pk_bf16_f32 v195, v250, v251
	s_nop 1
	v_mfma_f32_32x32x16_bf16 v[160:175], v[192:195], v[100:103], v[160:175]
	v_mfma_f32_32x32x16_bf16 v[176:191], v[192:195], v[132:135], v[176:191]
	ds_read_b128 v[196:199], v7 offset:128
	ds_read_b128 v[200:203], v7 offset:144
	s_waitcnt lgkmcnt(0)
	v_mul_f32_e32 v244, v48, v196
	v_mul_f32_e32 v245, v49, v197
	v_mul_f32_e32 v246, v50, v198
	v_mul_f32_e32 v247, v51, v199
	v_mul_f32_e32 v248, v52, v200
	v_mul_f32_e32 v249, v53, v201
	v_mul_f32_e32 v250, v54, v202
	v_mul_f32_e32 v251, v55, v203
	v_cvt_pk_bf16_f32 v192, v244, v245
	v_cvt_pk_bf16_f32 v193, v246, v247
	v_cvt_pk_bf16_f32 v194, v248, v249
	v_cvt_pk_bf16_f32 v195, v250, v251
	s_nop 1
	v_mfma_f32_32x32x16_bf16 v[160:175], v[192:195], v[104:107], v[160:175]
	v_mfma_f32_32x32x16_bf16 v[176:191], v[192:195], v[136:139], v[176:191]
	ds_read_b128 v[196:199], v7 offset:192
	ds_read_b128 v[200:203], v7 offset:208
	s_waitcnt lgkmcnt(0)
	v_mul_f32_e32 v244, v56, v196
	v_mul_f32_e32 v245, v57, v197
	v_mul_f32_e32 v246, v58, v198
	v_mul_f32_e32 v247, v59, v199
	v_mul_f32_e32 v248, v60, v200
	v_mul_f32_e32 v249, v61, v201
	v_mul_f32_e32 v250, v62, v202
	v_mul_f32_e32 v251, v63, v203
	v_cvt_pk_bf16_f32 v192, v244, v245
	v_cvt_pk_bf16_f32 v193, v246, v247
	v_cvt_pk_bf16_f32 v194, v248, v249
	v_cvt_pk_bf16_f32 v195, v250, v251
	s_nop 1
	v_mfma_f32_32x32x16_bf16 v[160:175], v[192:195], v[108:111], v[160:175]
	v_mfma_f32_32x32x16_bf16 v[176:191], v[192:195], v[140:143], v[176:191]
	s_cmp_lt_u32 s6, 2
	s_cbranch_scc1 .Lmy_sgu_mfma_done
	ds_read_b128 v[196:199], v7 offset:256
	ds_read_b128 v[200:203], v7 offset:272
	s_waitcnt lgkmcnt(0)
	v_mul_f32_e32 v244, v64, v196
	v_mul_f32_e32 v245, v65, v197
	v_mul_f32_e32 v246, v66, v198
	v_mul_f32_e32 v247, v67, v199
	v_mul_f32_e32 v248, v68, v200
	v_mul_f32_e32 v249, v69, v201
	v_mul_f32_e32 v250, v70, v202
	v_mul_f32_e32 v251, v71, v203
	v_cvt_pk_bf16_f32 v192, v244, v245
	v_cvt_pk_bf16_f32 v193, v246, v247
	v_cvt_pk_bf16_f32 v194, v248, v249
	v_cvt_pk_bf16_f32 v195, v250, v251
	s_nop 1
	v_mfma_f32_32x32x16_bf16 v[160:175], v[192:195], v[112:115], v[160:175]
	v_mfma_f32_32x32x16_bf16 v[176:191], v[192:195], v[144:147], v[176:191]
	ds_read_b128 v[196:199], v7 offset:320
	ds_read_b128 v[200:203], v7 offset:336
	s_waitcnt lgkmcnt(0)
	v_mul_f32_e32 v244, v72, v196
	v_mul_f32_e32 v245, v73, v197
	v_mul_f32_e32 v246, v74, v198
	v_mul_f32_e32 v247, v75, v199
	v_mul_f32_e32 v248, v76, v200
	v_mul_f32_e32 v249, v77, v201
	v_mul_f32_e32 v250, v78, v202
	v_mul_f32_e32 v251, v79, v203
	v_cvt_pk_bf16_f32 v192, v244, v245
	v_cvt_pk_bf16_f32 v193, v246, v247
	v_cvt_pk_bf16_f32 v194, v248, v249
	v_cvt_pk_bf16_f32 v195, v250, v251
	s_nop 1
	v_mfma_f32_32x32x16_bf16 v[160:175], v[192:195], v[116:119], v[160:175]
	v_mfma_f32_32x32x16_bf16 v[176:191], v[192:195], v[148:151], v[176:191]
	ds_read_b128 v[196:199], v7 offset:384
	ds_read_b128 v[200:203], v7 offset:400
	s_waitcnt lgkmcnt(0)
	v_mul_f32_e32 v244, v80, v196
	v_mul_f32_e32 v245, v81, v197
	v_mul_f32_e32 v246, v82, v198
	v_mul_f32_e32 v247, v83, v199
	v_mul_f32_e32 v248, v84, v200
	v_mul_f32_e32 v249, v85, v201
	v_mul_f32_e32 v250, v86, v202
	v_mul_f32_e32 v251, v87, v203
	v_cvt_pk_bf16_f32 v192, v244, v245
	v_cvt_pk_bf16_f32 v193, v246, v247
	v_cvt_pk_bf16_f32 v194, v248, v249
	v_cvt_pk_bf16_f32 v195, v250, v251
	s_nop 1
	v_mfma_f32_32x32x16_bf16 v[160:175], v[192:195], v[120:123], v[160:175]
	v_mfma_f32_32x32x16_bf16 v[176:191], v[192:195], v[152:155], v[176:191]
	ds_read_b128 v[196:199], v7 offset:448
	ds_read_b128 v[200:203], v7 offset:464
	s_waitcnt lgkmcnt(0)
	v_mul_f32_e32 v244, v88, v196
	v_mul_f32_e32 v245, v89, v197
	v_mul_f32_e32 v246, v90, v198
	v_mul_f32_e32 v247, v91, v199
	v_mul_f32_e32 v248, v92, v200
	v_mul_f32_e32 v249, v93, v201
	v_mul_f32_e32 v250, v94, v202
	v_mul_f32_e32 v251, v95, v203
	v_cvt_pk_bf16_f32 v192, v244, v245
	v_cvt_pk_bf16_f32 v193, v246, v247
	v_cvt_pk_bf16_f32 v194, v248, v249
	v_cvt_pk_bf16_f32 v195, v250, v251
	s_nop 1
	v_mfma_f32_32x32x16_bf16 v[160:175], v[192:195], v[124:127], v[160:175]
	v_mfma_f32_32x32x16_bf16 v[176:191], v[192:195], v[156:159], v[176:191]
.Lmy_sgu_mfma_done:
	s_nop 7
	s_nop 7
	v_fma_f32 v160, v160, v14, v16
	v_fma_f32 v176, v176, v15, v16
	v_fma_f32 v161, v161, v14, v17
	v_fma_f32 v177, v177, v15, v17
	v_fma_f32 v162, v162, v14, v18
	v_fma_f32 v178, v178, v15, v18
	v_fma_f32 v163, v163, v14, v19
	v_fma_f32 v179, v179, v15, v19
	v_fma_f32 v164, v164, v14, v20
	v_fma_f32 v180, v180, v15, v20
	v_fma_f32 v165, v165, v14, v21
	v_fma_f32 v181, v181, v15, v21
	v_fma_f32 v166, v166, v14, v22
	v_fma_f32 v182, v182, v15, v22
	v_fma_f32 v167, v167, v14, v23
	v_fma_f32 v183, v183, v15, v23
	v_fma_f32 v168, v168, v14, v24
	v_fma_f32 v184, v184, v15, v24
	v_fma_f32 v169, v169, v14, v25
	v_fma_f32 v185, v185, v15, v25
	v_fma_f32 v170, v170, v14, v26
	v_fma_f32 v186, v186, v15, v26
	v_fma_f32 v171, v171, v14, v27
	v_fma_f32 v187, v187, v15, v27
	v_fma_f32 v172, v172, v14, v28
	v_fma_f32 v188, v188, v15, v28
	v_fma_f32 v173, v173, v14, v29
	v_fma_f32 v189, v189, v15, v29
	v_fma_f32 v174, v174, v14, v30
	v_fma_f32 v190, v190, v15, v30
	v_fma_f32 v175, v175, v14, v31
	v_fma_f32 v191, v191, v15, v31
	ds_write_b32 v8, v160
	ds_write_b32 v8, v176 offset:128
	ds_write_b32 v8, v161 offset:528
	ds_write_b32 v8, v177 offset:656
	ds_write_b32 v8, v162 offset:1056
	ds_write_b32 v8, v178 offset:1184
	ds_write_b32 v8, v163 offset:1584
	ds_write_b32 v8, v179 offset:1712
	ds_write_b32 v8, v164 offset:4224
	ds_write_b32 v8, v180 offset:4352
	ds_write_b32 v8, v165 offset:4752
	ds_write_b32 v8, v181 offset:4880
	ds_write_b32 v8, v166 offset:5280
	ds_write_b32 v8, v182 offset:5408
	ds_write_b32 v8, v167 offset:5808
	ds_write_b32 v8, v183 offset:5936
	ds_write_b32 v8, v168 offset:8448
	ds_write_b32 v8, v184 offset:8576
	ds_write_b32 v8, v169 offset:8976
	ds_write_b32 v8, v185 offset:9104
	ds_write_b32 v8, v170 offset:9504
	ds_write_b32 v8, v186 offset:9632
	ds_write_b32 v8, v171 offset:10032
	ds_write_b32 v8, v187 offset:10160
	ds_write_b32 v8, v172 offset:12672
	ds_write_b32 v8, v188 offset:12800
	ds_write_b32 v8, v173 offset:13200
	ds_write_b32 v8, v189 offset:13328
	ds_write_b32 v8, v174 offset:13728
	ds_write_b32 v8, v190 offset:13856
	ds_write_b32 v8, v175 offset:14256
	ds_write_b32 v8, v191 offset:14384
	s_waitcnt lgkmcnt(0)
	s_barrier
	s_waitcnt vmcnt(0)
	ds_read_b128 v[212:215], v9
	ds_read_b128 v[216:219], v9 offset:16
	v_lshlrev_b32_e32 v244, 16, v228
	v_and_b32_e32 v245, 0xffff0000, v228
	v_lshlrev_b32_e32 v246, 16, v229
	v_and_b32_e32 v247, 0xffff0000, v229
	v_lshlrev_b32_e32 v248, 16, v230
	v_and_b32_e32 v249, 0xffff0000, v230
	v_lshlrev_b32_e32 v250, 16, v231
	v_and_b32_e32 v251, 0xffff0000, v231
	s_waitcnt lgkmcnt(0)
	v_mul_f32_e32 v244, v244, v212
	v_mul_f32_e32 v245, v245, v213
	v_mul_f32_e32 v246, v246, v214
	v_mul_f32_e32 v247, v247, v215
	v_mul_f32_e32 v248, v248, v216
	v_mul_f32_e32 v249, v249, v217
	v_mul_f32_e32 v250, v250, v218
	v_mul_f32_e32 v251, v251, v219
	v_cvt_pk_bf16_f32 v220, v244, v245
	v_cvt_pk_bf16_f32 v221, v246, v247
	v_cvt_pk_bf16_f32 v222, v248, v249
	v_cvt_pk_bf16_f32 v223, v250, v251
	global_store_dwordx4 v10, v[220:223], s[44:45]
	ds_read_b128 v[212:215], v9 offset:16896
	ds_read_b128 v[216:219], v9 offset:16912
	v_lshlrev_b32_e32 v244, 16, v232
	v_and_b32_e32 v245, 0xffff0000, v232
	v_lshlrev_b32_e32 v246, 16, v233
	v_and_b32_e32 v247, 0xffff0000, v233
	v_lshlrev_b32_e32 v248, 16, v234
	v_and_b32_e32 v249, 0xffff0000, v234
	v_lshlrev_b32_e32 v250, 16, v235
	v_and_b32_e32 v251, 0xffff0000, v235
	s_waitcnt lgkmcnt(0)
	v_mul_f32_e32 v244, v244, v212
	v_mul_f32_e32 v245, v245, v213
	v_mul_f32_e32 v246, v246, v214
	v_mul_f32_e32 v247, v247, v215
	v_mul_f32_e32 v248, v248, v216
	v_mul_f32_e32 v249, v249, v217
	v_mul_f32_e32 v250, v250, v218
	v_mul_f32_e32 v251, v251, v219
	v_cvt_pk_bf16_f32 v220, v244, v245
	v_cvt_pk_bf16_f32 v221, v246, v247
	v_cvt_pk_bf16_f32 v222, v248, v249
	v_cvt_pk_bf16_f32 v223, v250, v251
	global_store_dwordx4 v11, v[220:223], s[44:45]
	ds_read_b128 v[212:215], v9 offset:33792
	ds_read_b128 v[216:219], v9 offset:33808
	v_lshlrev_b32_e32 v244, 16, v236
	v_and_b32_e32 v245, 0xffff0000, v236
	v_lshlrev_b32_e32 v246, 16, v237
	v_and_b32_e32 v247, 0xffff0000, v237
	v_lshlrev_b32_e32 v248, 16, v238
	v_and_b32_e32 v249, 0xffff0000, v238
	v_lshlrev_b32_e32 v250, 16, v239
	v_and_b32_e32 v251, 0xffff0000, v239
	s_waitcnt lgkmcnt(0)
	v_mul_f32_e32 v244, v244, v212
	v_mul_f32_e32 v245, v245, v213
	v_mul_f32_e32 v246, v246, v214
	v_mul_f32_e32 v247, v247, v215
	v_mul_f32_e32 v248, v248, v216
	v_mul_f32_e32 v249, v249, v217
	v_mul_f32_e32 v250, v250, v218
	v_mul_f32_e32 v251, v251, v219
	v_cvt_pk_bf16_f32 v220, v244, v245
	v_cvt_pk_bf16_f32 v221, v246, v247
	v_cvt_pk_bf16_f32 v222, v248, v249
	v_cvt_pk_bf16_f32 v223, v250, v251
	global_store_dwordx4 v12, v[220:223], s[44:45]
	ds_read_b128 v[212:215], v9 offset:50688
	ds_read_b128 v[216:219], v9 offset:50704
	v_lshlrev_b32_e32 v244, 16, v240
	v_and_b32_e32 v245, 0xffff0000, v240
	v_lshlrev_b32_e32 v246, 16, v241
	v_and_b32_e32 v247, 0xffff0000, v241
	v_lshlrev_b32_e32 v248, 16, v242
	v_and_b32_e32 v249, 0xffff0000, v242
	v_lshlrev_b32_e32 v250, 16, v243
	v_and_b32_e32 v251, 0xffff0000, v243
	s_waitcnt lgkmcnt(0)
	v_mul_f32_e32 v244, v244, v212
	v_mul_f32_e32 v245, v245, v213
	v_mul_f32_e32 v246, v246, v214
	v_mul_f32_e32 v247, v247, v215
	v_mul_f32_e32 v248, v248, v216
	v_mul_f32_e32 v249, v249, v217
	v_mul_f32_e32 v250, v250, v218
	v_mul_f32_e32 v251, v251, v219
	v_cvt_pk_bf16_f32 v220, v244, v245
	v_cvt_pk_bf16_f32 v221, v246, v247
	v_cvt_pk_bf16_f32 v222, v248, v249
	v_cvt_pk_bf16_f32 v223, v250, v251
	global_store_dwordx4 v13, v[220:223], s[44:45]
	s_add_i32 s101, s101, s42
	s_barrier
	s_cmpk_lt_u32 s101, 0x800
	s_cbranch_scc1 .Lmy_sgu_unit
.Lmy_sgu_done:
	v_mov_b32_e32 v106, v226
	s_cmpk_gt_i32 s101, 0x8ff
	s_nop 0
	v_readfirstlane_b32 s8, v106
	s_cbranch_scc1 .LBB0_1528
	s_add_u32 s20, s38, 0xc500000
	s_addc_u32 s21, s39, 0
	s_add_u32 s22, s38, 0x8400000
	s_addc_u32 s23, s39, 0
	s_add_u32 s24, s38, 0x10700000
	s_addc_u32 s25, s39, 0
	s_bfe_u32 s9, s8, 0x20006
	s_cmp_eq_u32 s9, 0
	s_cselect_b64 s[30:31], -1, 0
	s_cmp_lt_u32 s9, 2
	s_cselect_b32 s3, 4, 8
	s_ashr_i32 s8, s8, 2
	s_load_dwordx4 s[16:19], s[0:1], 0xc0
	s_load_dwordx2 s[26:27], s[0:1], 0xd0
	v_and_b32_e32 v2, 31, v106
	v_ashrrev_i32_e32 v107, 31, v106
	s_andn2_b32 s8, s8, 63
	v_lshl_add_u64 v[0:1], v[106:107], 2, s[38:39]
	s_mov_b64 s[10:11], 0x3000000
	v_or_b32_e32 v107, s8, v2
	s_lshl_b32 s8, s9, 5
	v_lshl_add_u64 v[108:109], v[0:1], 0, s[10:11]
	v_or_b32_e32 v0, s8, v2
	v_bfe_u32 v3, v106, 5, 1
	v_lshlrev_b32_e32 v32, 9, v0
	v_mov_b32_e32 v33, 0
	s_waitcnt lgkmcnt(0)
	v_lshl_add_u64 v[0:1], s[18:19], 0, v[32:33]
	v_lshlrev_b32_e32 v32, 5, v3
	v_mov_b32_e32 v34, v33
	v_mov_b32_e32 v35, v33
	v_mov_b32_e32 v36, v33
	v_mov_b32_e32 v37, v33
	v_mov_b32_e32 v38, v33
	v_mov_b32_e32 v39, v33
	s_movk_i32 s6, 0x80
	v_lshlrev_b32_e32 v2, 3, v3
	v_lshl_add_u64 v[110:111], v[0:1], 0, v[32:33]
	v_lshl_or_b32 v112, v3, 2, s8
	v_add_u32_e32 v151, 0, v32
	s_movk_i32 s8, 0x7ff
	v_mov_b32_e32 v32, v33
	v_mov_b64_e32 v[40:41], v[38:39]
	s_mov_b32 s29, 0
	v_cmp_gt_i32_e64 s[6:7], s6, v106
	v_lshl_add_u32 v150, v106, 2, 0
	v_cmp_lt_i32_e64 s[8:9], s8, v106
	v_and_b32_e32 v152, 0x7f, v106
	v_mov_b32_e32 v113, v33
	v_or_b32_e32 v114, 1, v112
	v_mov_b32_e32 v115, v33
	v_or_b32_e32 v116, 2, v112
	v_mov_b32_e32 v117, v33
	v_or_b32_e32 v118, 3, v112
	v_mov_b32_e32 v119, v33
	v_or_b32_e32 v120, 8, v112
	v_mov_b32_e32 v121, v33
	v_or_b32_e32 v122, 9, v112
	v_mov_b32_e32 v123, v33
	v_or_b32_e32 v124, 10, v112
	v_mov_b32_e32 v125, v33
	v_or_b32_e32 v126, 11, v112
	v_mov_b32_e32 v127, v33
	s_waitcnt vmcnt(0)
	v_or_b32_e32 v128, 16, v112
	v_mov_b32_e32 v129, v33
	v_or_b32_e32 v130, 17, v112
	v_mov_b32_e32 v131, v33
	v_or_b32_e32 v132, 18, v112
	v_mov_b32_e32 v133, v33
	v_or_b32_e32 v134, 19, v112
	v_mov_b32_e32 v135, v33
	v_or_b32_e32 v136, 24, v112
	v_mov_b32_e32 v137, v33
	v_or_b32_e32 v138, 25, v112
	v_mov_b32_e32 v139, v33
	v_or_b32_e32 v140, 26, v112
	v_mov_b32_e32 v141, v33
	v_or_b32_e32 v142, 27, v112
	v_mov_b32_e32 v143, v33
	s_mov_b32 s50, 0x10600
	v_lshlrev_b32_e32 v144, 1, v2
	v_mov_b32_e32 v153, 0x358637bd
	s_movk_i32 s51, 0x5ff
	s_mov_b32 s52, s101
	v_mov_b64_e32 v[38:39], v[36:37]
	v_mov_b64_e32 v[36:37], v[34:35]
	v_mov_b64_e32 v[34:35], v[32:33]
	s_branch .LBB0_1409
